# attention: softmax row-sum adds moved into the QK MFMA shadow and next-tile row-max chain interleaved into the PV MFMA stream for non-diagonal tiles
# speedup vs baseline: 1.0039x; 1.0039x over previous
; __device__ __forceinline__ void finishSM(f32x16& p0, f32x16& p1, float alpha, float& l_reg, bf16x8& pa0, bf16x8& pa1, bf16x8& pa2, bf16x8& pa3) {
; #pragma unroll
;     for (int r = 0; r < 16; ++r) p1[r] = __builtin_amdgcn_exp2f(p1[r]);
;     float ps = 0;
; #pragma unroll
;     for (int r = 0; r < 16; ++r) ps += p0[r];
; #pragma unroll
;     for (int r = 0; r < 16; ++r) ps += p1[r];
;     { auto rr = __builtin_amdgcn_permlane32_swap(__float_as_uint(ps), __float_as_uint(ps), false, false);
;       ps = __uint_as_float(rr[0]) + __uint_as_float(rr[1]); }
;     l_reg = l_reg * alpha + ps;
;     ...
;     PK4(p0, 0, pa0); PK4(p0, 8, pa1); PK4(p1, 0, pa2); PK4(p1, 8, pa3);
;     ...
; }
; template <int KB>
; __device__ __forceinline__ void qkt(f32x16& p0, f32x16& p1, const char* K_lds, int r32, int hi, const bf16x8* qr, const char* qbase) {
;     p0 = f32x16{}; p1 = f32x16{};
;     const char* kbp = K_lds + KB * SHM_K + r32 * KROW + hi * 16;
; #pragma unroll
;     for (int d0 = 0; d0 < 12; ++d0) { const char* a = kbp + d0 * 32;
;         bf16x8 b0 = *reinterpret_cast<const bf16x8*>(a);
;         bf16x8 b1 = *reinterpret_cast<const bf16x8*>(a + 32 * KROW);
;         const bf16x8 qf = d0 < 4 ? qr[d0 & 3] : *reinterpret_cast<const bf16x8*>(qbase + (d0 - 4) * 32);
;         p0 = __builtin_amdgcn_mfma_f32_32x32x16_bf16(b0, qf, p0, 0, 0, 0);
;         p1 = __builtin_amdgcn_mfma_f32_32x32x16_bf16(b1, qf, p1, 0, 0, 0); }
; }
.LBB0_1481:
	ds_read_b128 v[64:67], v202 offset:58368
	s_waitcnt vmcnt(0)
	ds_read_b128 v[100:103], v202 offset:58400
	v_exp_f32_e32 v112, v172
	v_exp_f32_e32 v113, v173
	v_exp_f32_e32 v114, v170
	s_waitcnt lgkmcnt(1)
	v_mfma_f32_32x32x16_bf16 v[84:99], v[64:67], v[142:145], 0
	ds_read_b128 v[64:67], v206 offset:12800
	ds_read_b128 v[104:107], v206 offset:12832
	v_exp_f32_e32 v115, v171
	v_exp_f32_e32 v116, v168
	v_exp_f32_e32 v117, v169
	v_exp_f32_e32 v118, v166
	v_exp_f32_e32 v119, v167
	s_waitcnt lgkmcnt(1)
	v_mfma_f32_32x32x16_bf16 v[68:83], v[64:67], v[142:145], 0
	v_mfma_f32_32x32x16_bf16 v[84:99], v[100:103], v[138:141], v[84:99]
	ds_read_b128 v[64:67], v202 offset:58432
	ds_read_b128 v[100:103], v206 offset:12864
	v_add_f32_e32 v255, 0, v233
	v_add_f32_e32 v255, v235, v255
	s_waitcnt lgkmcnt(2)
	v_mfma_f32_32x32x16_bf16 v[68:83], v[104:107], v[138:141], v[68:83]
	v_add_f32_e32 v255, v231, v255
	v_add_f32_e32 v255, v234, v255
	s_waitcnt lgkmcnt(1)
	v_mfma_f32_32x32x16_bf16 v[84:99], v[64:67], v[134:137], v[84:99]
	v_add_f32_e32 v255, v223, v255
	v_add_f32_e32 v255, v232, v255
	s_waitcnt lgkmcnt(0)
	v_mfma_f32_32x32x16_bf16 v[68:83], v[100:103], v[134:137], v[68:83]
	ds_read_b128 v[64:67], v202 offset:58464
	ds_read_b128 v[100:103], v206 offset:12896
	v_add_f32_e32 v255, v221, v255
	v_add_f32_e32 v255, v222, v255
	s_waitcnt lgkmcnt(1)
	v_mfma_f32_32x32x16_bf16 v[84:99], v[64:67], v[130:133], v[84:99]
	v_add_f32_e32 v255, v217, v255
	v_add_f32_e32 v255, v220, v255
	s_waitcnt lgkmcnt(0)
	v_mfma_f32_32x32x16_bf16 v[68:83], v[100:103], v[130:133], v[68:83]
	ds_read_b128 v[64:67], v202 offset:58496
	ds_read_b128 v[100:103], v206 offset:12928
	ds_read_b128 v[104:107], v201
	ds_read_b128 v[108:111], v201 offset:32
	v_add_f32_e32 v255, v215, v255
	v_add_f32_e32 v255, v218, v255
	s_waitcnt lgkmcnt(1)
	v_mfma_f32_32x32x16_bf16 v[84:99], v[64:67], v[104:107], v[84:99]
	v_mfma_f32_32x32x16_bf16 v[68:83], v[100:103], v[104:107], v[68:83]
	ds_read_b128 v[64:67], v202 offset:58528
	ds_read_b128 v[100:103], v206 offset:12960
	v_add_f32_e32 v255, v213, v255
	v_add_f32_e32 v255, v219, v255
	s_waitcnt lgkmcnt(1)
	v_mfma_f32_32x32x16_bf16 v[84:99], v[64:67], v[108:111], v[84:99]
	v_add_f32_e32 v255, v214, v255
	v_add_f32_e32 v255, v216, v255
	s_waitcnt lgkmcnt(0)
	v_mfma_f32_32x32x16_bf16 v[68:83], v[100:103], v[108:111], v[68:83]
	ds_read_b128 v[64:67], v202 offset:58560
	ds_read_b128 v[100:103], v206 offset:12992
	ds_read_b128 v[104:107], v201 offset:64
	v_exp_f32_e32 v108, v176
	v_exp_f32_e32 v109, v177
	v_exp_f32_e32 v110, v174
	v_exp_f32_e32 v111, v175
	v_add_f32_e32 v255, v112, v255
	v_add_f32_e32 v255, v113, v255
	s_waitcnt lgkmcnt(0)
	v_mfma_f32_32x32x16_bf16 v[84:99], v[64:67], v[104:107], v[84:99]
	v_mfma_f32_32x32x16_bf16 v[68:83], v[100:103], v[104:107], v[68:83]
	ds_read_b128 v[64:67], v202 offset:58592
	ds_read_b128 v[100:103], v206 offset:13024
	ds_read_b128 v[104:107], v201 offset:96
	v_add_f32_e32 v255, v114, v255
	v_add_f32_e32 v255, v115, v255
	s_waitcnt lgkmcnt(0)
	v_mfma_f32_32x32x16_bf16 v[84:99], v[64:67], v[104:107], v[84:99]
	v_mfma_f32_32x32x16_bf16 v[68:83], v[100:103], v[104:107], v[68:83]
	ds_read_b128 v[64:67], v202 offset:58624
	ds_read_b128 v[100:103], v206 offset:13056
	ds_read_b128 v[104:107], v201 offset:128
	v_add_f32_e32 v255, v116, v255
	v_add_f32_e32 v255, v117, v255
	s_waitcnt lgkmcnt(0)
	v_mfma_f32_32x32x16_bf16 v[84:99], v[64:67], v[104:107], v[84:99]
	v_mfma_f32_32x32x16_bf16 v[68:83], v[100:103], v[104:107], v[68:83]
	ds_read_b128 v[64:67], v202 offset:58656
	ds_read_b128 v[100:103], v206 offset:13088
	ds_read_b128 v[104:107], v201 offset:160
	v_add_f32_e32 v255, v118, v255
	v_add_f32_e32 v255, v119, v255
	s_waitcnt lgkmcnt(0)
	v_mfma_f32_32x32x16_bf16 v[84:99], v[64:67], v[104:107], v[84:99]
	v_mfma_f32_32x32x16_bf16 v[68:83], v[100:103], v[104:107], v[68:83]
	ds_read_b128 v[64:67], v202 offset:58688
	ds_read_b128 v[100:103], v206 offset:13120
	ds_read_b128 v[104:107], v201 offset:192
	v_add_f32_e32 v255, v108, v255
	v_add_f32_e32 v255, v109, v255
	s_waitcnt lgkmcnt(0)
	v_mfma_f32_32x32x16_bf16 v[84:99], v[64:67], v[104:107], v[84:99]
	v_mfma_f32_32x32x16_bf16 v[68:83], v[100:103], v[104:107], v[68:83]
	ds_read_b128 v[64:67], v202 offset:58720
	ds_read_b128 v[100:103], v206 offset:13152
	ds_read_b128 v[104:107], v201 offset:224
	v_add_f32_e32 v255, v110, v255
	v_add_f32_e32 v255, v111, v255
	s_waitcnt lgkmcnt(0)
	v_mfma_f32_32x32x16_bf16 v[84:99], v[64:67], v[104:107], v[84:99]
	v_mfma_f32_32x32x16_bf16 v[68:83], v[100:103], v[104:107], v[68:83]
	v_exp_f32_e32 v104, v180
	v_exp_f32_e32 v105, v181
	v_exp_f32_e32 v106, v178
	v_exp_f32_e32 v107, v179
	v_add_f32_e32 v255, v104, v255
	v_add_f32_e32 v255, v105, v255
	v_add_f32_e32 v255, v106, v255
	v_add_f32_e32 v210, v107, v255
	v_mov_b32_e32 v211, v210
	s_nop 1
	v_permlane32_swap_b32_e32 v210, v211
	v_cvt_pk_bf16_f32 v64, v233, v235
	v_cvt_pk_bf16_f32 v65, v231, v234
	v_cvt_pk_bf16_f32 v66, v223, v232
	v_cvt_pk_bf16_f32 v67, v221, v222
	v_cvt_pk_bf16_f32 v100, v217, v220
	v_cvt_pk_bf16_f32 v101, v215, v218
	v_cvt_pk_bf16_f32 v102, v213, v219
	v_cvt_pk_bf16_f32 v103, v214, v216
	v_cvt_pk_bf16_f32 v104, v104, v105
	v_cvt_pk_bf16_f32 v105, v106, v107
	v_cvt_pk_bf16_f32 v106, v108, v109
	v_cvt_pk_bf16_f32 v107, v110, v111
	v_cvt_pk_bf16_f32 v108, v112, v113
	v_cvt_pk_bf16_f32 v109, v114, v115
	v_cvt_pk_bf16_f32 v110, v116, v117
	v_cvt_pk_bf16_f32 v111, v118, v119
	s_nop 0
	v_permlane32_swap_b32_e32 v64, v66
	v_permlane32_swap_b32_e32 v65, v67
	v_permlane32_swap_b32_e32 v100, v102
	v_permlane32_swap_b32_e32 v101, v103
	v_permlane32_swap_b32_e32 v104, v106
	v_permlane32_swap_b32_e32 v105, v107
	v_permlane32_swap_b32_e32 v108, v110
	v_permlane32_swap_b32_e32 v109, v111
	v_add_u32_e32 v213, s31, v183
	v_add_u32_e32 v112, 0x80, v213
	v_min_u32_e32 v114, 0x100f, v112
	v_add_u32_e32 v113, 0x4080, v213
	v_add_u32_e32 v114, s14, v114
	v_cmp_gt_i32_e32 vcc, 16, v112
	s_nop 1
	v_cndmask_b32_e32 v112, v114, v113, vcc
	v_ashrrev_i32_e32 v113, 31, v112
	v_mad_i64_i32 v[114:115], s[0:1], v112, s33, v[184:185]
	v_lshlrev_b64 v[112:113], 12, v[112:113]
	v_lshl_add_u64 v[112:113], v[186:187], 0, v[112:113]
	flat_load_dwordx4 v[146:149], v[112:113] offset:128
	flat_load_dwordx4 v[150:153], v[114:115]
	flat_load_dwordx4 v[154:157], v[114:115] offset:128
	flat_load_dwordx4 v[162:165], v[112:113]
	flat_load_dwordx4 v[158:161], v[114:115] offset:256
	s_add_i32 s0, s31, 0x7f
	s_cmp_le_i32 s0, s30
	s_cbranch_scc1 .La_pvmax1
; __device__ __forceinline__ void mask_tile(f32x16& p0, f32x16& p1, int dq) {
;     const float NEG = -__builtin_inff();
; #pragma unroll
;     for (int r = 0; r < 16; ++r) {
;         const int c = (r & 3) + 8 * (r >> 2);
;         if (dq - c < 0) p0[r] = NEG;
;         if (dq - c - 32 < 0) p1[r] = NEG;
;     }
; }
; template <int VB>
; __device__ __forceinline__ void pv_tile(f32x16* o, int vb0, bf16x8 pa0, bf16x8 pa1, bf16x8 pa2, bf16x8 pa3) {
;     ...
;     PV_D0(0); PV_D0(1); PV_D0(2); PV_D0(3);
	ds_read_b64_tr_b16 v[112:113], v199 offset:0
	ds_read_b64_tr_b16 v[114:115], v199 offset:0x800
	ds_read_b64_tr_b16 v[116:117], v199 offset:0x1000
	ds_read_b64_tr_b16 v[118:119], v199 offset:0x1800
	ds_read_b64_tr_b16 v[120:121], v199 offset:0x2000
	ds_read_b64_tr_b16 v[122:123], v199 offset:0x2800
	ds_read_b64_tr_b16 v[124:125], v199 offset:0x3000
	ds_read_b64_tr_b16 v[126:127], v199 offset:0x3800
	s_waitcnt lgkmcnt(0)
	s_nop 0
	v_mfma_f32_32x32x16_bf16 v[48:63], v[64:67], v[112:115], v[48:63]
	ds_read_b64_tr_b16 v[112:113], v199 offset:0x200
	ds_read_b64_tr_b16 v[114:115], v199 offset:0xa00
	v_mfma_f32_32x32x16_bf16 v[48:63], v[100:103], v[116:119], v[48:63]
	ds_read_b64_tr_b16 v[116:117], v199 offset:0x1200
	ds_read_b64_tr_b16 v[118:119], v199 offset:0x1a00
	v_mfma_f32_32x32x16_bf16 v[48:63], v[104:107], v[120:123], v[48:63]
	ds_read_b64_tr_b16 v[120:121], v199 offset:0x2200
	ds_read_b64_tr_b16 v[122:123], v199 offset:0x2a00
	v_mfma_f32_32x32x16_bf16 v[48:63], v[108:111], v[124:127], v[48:63]
	ds_read_b64_tr_b16 v[124:125], v199 offset:0x3200
	ds_read_b64_tr_b16 v[126:127], v199 offset:0x3a00
	s_waitcnt lgkmcnt(0)
	v_mfma_f32_32x32x16_bf16 v[32:47], v[64:67], v[112:115], v[32:47]
	ds_read_b64_tr_b16 v[112:113], v199 offset:0x400
	ds_read_b64_tr_b16 v[114:115], v199 offset:0xc00
	v_mfma_f32_32x32x16_bf16 v[32:47], v[100:103], v[116:119], v[32:47]
	ds_read_b64_tr_b16 v[116:117], v199 offset:0x1400
	ds_read_b64_tr_b16 v[118:119], v199 offset:0x1c00
	v_mfma_f32_32x32x16_bf16 v[32:47], v[104:107], v[120:123], v[32:47]
	ds_read_b64_tr_b16 v[120:121], v199 offset:0x2400
	ds_read_b64_tr_b16 v[122:123], v199 offset:0x2c00
	v_mfma_f32_32x32x16_bf16 v[32:47], v[108:111], v[124:127], v[32:47]
	ds_read_b64_tr_b16 v[124:125], v199 offset:0x3400
	ds_read_b64_tr_b16 v[126:127], v199 offset:0x3c00
	s_waitcnt lgkmcnt(0)
	v_mfma_f32_32x32x16_bf16 v[16:31], v[64:67], v[112:115], v[16:31]
	ds_read_b64_tr_b16 v[112:113], v199 offset:0x600
	ds_read_b64_tr_b16 v[114:115], v199 offset:0xe00
	v_mfma_f32_32x32x16_bf16 v[16:31], v[100:103], v[116:119], v[16:31]
	ds_read_b64_tr_b16 v[116:117], v199 offset:0x1600
	ds_read_b64_tr_b16 v[118:119], v199 offset:0x1e00
	v_mfma_f32_32x32x16_bf16 v[16:31], v[104:107], v[120:123], v[16:31]
	ds_read_b64_tr_b16 v[120:121], v199 offset:0x2600
	ds_read_b64_tr_b16 v[122:123], v199 offset:0x2e00
	v_mfma_f32_32x32x16_bf16 v[16:31], v[108:111], v[124:127], v[16:31]
	ds_read_b64_tr_b16 v[124:125], v199 offset:0x3600
	ds_read_b64_tr_b16 v[126:127], v199 offset:0x3e00
	s_waitcnt lgkmcnt(0)
	v_mfma_f32_32x32x16_bf16 v[0:15], v[64:67], v[112:115], v[0:15]
	s_add_i32 s0, s31, 0x7f
	s_cmp_le_i32 s0, s30
	v_mfma_f32_32x32x16_bf16 v[0:15], v[100:103], v[116:119], v[0:15]
	v_mfma_f32_32x32x16_bf16 v[0:15], v[104:107], v[120:123], v[0:15]
	v_mfma_f32_32x32x16_bf16 v[0:15], v[108:111], v[124:127], v[0:15]
	s_cbranch_scc1 .LBB0_1483
	v_add_u32_e32 v64, 64, v209
	v_cmp_gt_i32_e64 s[96:97], 26, v64
	v_cmp_gt_i32_e32 vcc, 27, v64
	v_cmp_gt_i32_e64 s[94:95], 25, v64
	v_cmp_gt_i32_e64 s[92:93], 24, v64
	v_cndmask_b32_e32 v99, v99, v228, vcc
	s_and_b64 vcc, vcc, s[96:97]
	v_cndmask_b32_e32 v98, v98, v228, vcc
	s_and_b64 vcc, vcc, s[94:95]
	v_cmp_gt_i32_e64 s[90:91], 19, v64
	v_cndmask_b32_e32 v97, v97, v228, vcc
	s_and_b64 vcc, vcc, s[92:93]
	v_cmp_gt_i32_e64 s[88:89], 18, v64
	v_cndmask_b32_e32 v96, v96, v228, vcc
	s_and_b64 vcc, vcc, s[90:91]
	v_cmp_gt_i32_e64 s[86:87], 17, v64
	v_cndmask_b32_e32 v95, v95, v228, vcc
	s_and_b64 vcc, vcc, s[88:89]
	v_cmp_gt_i32_e64 s[84:85], 16, v64
	v_cndmask_b32_e32 v94, v94, v228, vcc
	s_and_b64 vcc, vcc, s[86:87]
	v_cmp_gt_i32_e64 s[82:83], 11, v64
	v_cndmask_b32_e32 v93, v93, v228, vcc
	s_and_b64 vcc, vcc, s[84:85]
	v_cmp_gt_i32_e64 s[80:81], 10, v64
	v_cndmask_b32_e32 v92, v92, v228, vcc
	s_and_b64 vcc, vcc, s[82:83]
	v_cmp_gt_i32_e64 s[78:79], 9, v64
	v_cndmask_b32_e32 v91, v91, v228, vcc
	s_and_b64 vcc, vcc, s[80:81]
	v_cmp_gt_i32_e64 s[76:77], 8, v64
	v_cndmask_b32_e32 v90, v90, v228, vcc
	s_and_b64 vcc, vcc, s[78:79]
	v_cmp_gt_i32_e64 s[74:75], 3, v64
	v_cndmask_b32_e32 v89, v89, v228, vcc
	s_and_b64 vcc, vcc, s[76:77]
	v_cmp_gt_i32_e64 s[72:73], 2, v64
	v_cndmask_b32_e32 v88, v88, v228, vcc
	s_and_b64 vcc, vcc, s[74:75]
	v_cmp_gt_i32_e64 s[70:71], 1, v64
	v_cndmask_b32_e32 v87, v87, v228, vcc
	s_and_b64 vcc, vcc, s[72:73]
	v_cmp_gt_i32_e64 s[4:5], 0, v64
	v_cndmask_b32_e32 v86, v86, v228, vcc
	s_and_b64 vcc, vcc, s[70:71]
	v_cndmask_b32_e32 v85, v85, v228, vcc
	s_and_b64 vcc, vcc, s[4:5]
	v_cmp_gt_i32_e64 s[68:69], 58, v64
	v_cndmask_b32_e32 v84, v84, v228, vcc
	v_cmp_gt_i32_e32 vcc, 59, v64
	v_cmp_gt_i32_e64 s[66:67], 57, v64
	v_cmp_gt_i32_e64 s[64:65], 56, v64
	v_cndmask_b32_e32 v83, v83, v228, vcc
	s_and_b64 vcc, vcc, s[68:69]
	v_cndmask_b32_e32 v82, v82, v228, vcc
	s_and_b64 vcc, vcc, s[66:67]
	v_cmp_gt_i32_e64 s[62:63], 51, v64
	v_cndmask_b32_e32 v81, v81, v228, vcc
	s_and_b64 vcc, vcc, s[64:65]
	v_cmp_gt_i32_e64 s[60:61], 50, v64
	v_cndmask_b32_e32 v80, v80, v228, vcc
	s_and_b64 vcc, vcc, s[62:63]
	v_cmp_gt_i32_e64 s[58:59], 49, v64
	v_cndmask_b32_e32 v79, v79, v228, vcc
	s_and_b64 vcc, vcc, s[60:61]
	v_cmp_gt_i32_e64 s[56:57], 48, v64
	v_cndmask_b32_e32 v78, v78, v228, vcc
	s_and_b64 vcc, vcc, s[58:59]
	v_cmp_gt_i32_e64 s[54:55], 43, v64
	v_cndmask_b32_e32 v77, v77, v228, vcc
	s_and_b64 vcc, vcc, s[56:57]
	v_cmp_gt_i32_e64 s[52:53], 42, v64
	v_cndmask_b32_e32 v76, v76, v228, vcc
	s_and_b64 vcc, vcc, s[54:55]
	v_cmp_gt_i32_e64 s[50:51], 41, v64
	v_cndmask_b32_e32 v75, v75, v228, vcc
	s_and_b64 vcc, vcc, s[52:53]
	v_cmp_gt_i32_e64 s[46:47], 40, v64
	v_cndmask_b32_e32 v74, v74, v228, vcc
	s_and_b64 vcc, vcc, s[50:51]
	v_cmp_gt_i32_e64 s[44:45], 35, v64
	v_cndmask_b32_e32 v73, v73, v228, vcc
	s_and_b64 vcc, vcc, s[46:47]
	v_cmp_gt_i32_e64 s[42:43], 34, v64
	v_cndmask_b32_e32 v72, v72, v228, vcc
	s_and_b64 vcc, vcc, s[44:45]
	v_cmp_gt_i32_e64 s[0:1], 33, v64
	v_cndmask_b32_e32 v71, v71, v228, vcc
	s_and_b64 vcc, vcc, s[42:43]
	v_cmp_gt_i32_e64 s[6:7], 32, v64
	v_cndmask_b32_e32 v70, v70, v228, vcc
	s_and_b64 vcc, vcc, s[0:1]
	v_cndmask_b32_e32 v69, v69, v228, vcc
	s_and_b64 vcc, vcc, s[6:7]
	s_mov_b32 s97, 0x41000000
	v_cndmask_b32_e32 v68, v68, v228, vcc

; #define SBAR() __builtin_amdgcn_sched_barrier(0)
; #define VMW() asm volatile("s_waitcnt vmcnt(0)" ::: "memory")
; #define SLOAD(R_, k0) do { const size_t tr_ = (size_t)tokrow((R_).b, (k0) + srow); const bf16_t* kp_ = (const bf16_t*)(T.ws + OFF_KF) + tr_ * 3072 + (R_).h * 192 + c0 * 8; const bf16_t* vp_ = (const bf16_t*)(T.ws + OFF_V) + tr_ * 2048 + (R_).h * 128 + c0 * 8; \
;         S.st_v0 = ld8(vp_); S.st_v1 = ld8(vp_ + 64); S.st_k0 = ld8(kp_); S.st_k1 = ld8(kp_ + 64); S.st_k2 = ld8(kp_ + 128); } while (0)
; #define SWRITE_HV(bf) do { *(bf16x8*)(V_lds + (bf) * SHM_V + vst0) = S.st_v0; *(bf16x8*)(V_lds + (bf) * SHM_V + vst0 + 1024) = S.st_v1; } while (0)
; #define SWRITE_H(bf) do { SWRITE_HV(bf); SWRITE_HK(bf); } while (0)
; #define MASKT(P0_, P1_, t) do { const int kb_ = KBASE(t); if (kb_ + KVBLK - 1 > qlo) mask_tile(P0_, P1_, qm - kb_); } while (0)
; __device__ __forceinline__ void partialSM(f32x16& p0, f32x16& p1, float& m_reg, float& mn, float& alpha) {
;     ...
;     const float mnL = -mn * C2;
; #pragma unroll
;     for (int r = 0; r < 16; ++r) p0[r] = fmaf(p0[r], C2, mnL);
; #pragma unroll
;     for (int r = 0; r < 16; ++r) p1[r] = fmaf(p1[r], C2, mnL);
; #pragma unroll
;     for (int r = 0; r < 16; ++r) p0[r] = __builtin_amdgcn_exp2f(p0[r]);
; __device__ __forceinline__ void attn_block(const Ref& cur, const Ref& nxt, const Tens& T, char* lds, Seam& S, bool nostore) {
;     ...
;     f32x16 pA0, pA1, pB0, pB1; float mnA, mnB, alA, alB; bf16x8 pa0, pa1, pa2, pa3;
;     char* qbase = lds + LDS_QR + wid * QR_WAVE + r32 * QR_ROW + hi * 16;
; #pragma unroll
;     for (int j = 0; j < 8; ++j) *(bf16x8*)(qbase + j * 32) = S.qr[4 + j];
;     SBAR();
;     SWRITE_HV(0); SBAR();
;     if (NT > 1) { SLOAD(cur, KBASE(1)); }
;     SBAR(); qkt<0>(pA0, pA1, K_lds, r32, hi, S.qr, qbase);
;     MASKT(pA0, pA1, 0); partialSM(pA0, pA1, m_reg, mnA, alA);
;     if (NT > 1) { VMW(); SWRITE_H(1); }
;     __syncthreads();
.La_b1_1:
	s_waitcnt lgkmcnt(0)
	s_barrier
	s_waitcnt vmcnt(0)
	v_cndmask_b32_e64 v212, v65, 1.0, s[42:43]
	v_cmp_gt_f32_e32 vcc, 1.0, v212
	s_waitcnt vmcnt(0)
	ds_write_b128 v204, v[162:165]
	ds_write_b128 v204, v[146:149] offset:1024
	ds_write_b128 v192, v[150:153] offset:32768
	ds_write_b128 v192, v[154:157] offset:32896
	ds_write_b128 v192, v[158:161] offset:33024
	s_cbranch_vccz .LBB0_1487
	s_and_saveexec_b64 s[0:1], s[40:41]
	ds_write_b32 v198, v212 offset:128
	s_or_b64 exec, exec, s[0:1]
	s_waitcnt lgkmcnt(0)
	ds_read_b128 v[100:103], v193 offset:224
	ds_read_b128 v[104:107], v193 offset:192
	ds_read_b128 v[108:111], v193 offset:160
	ds_read_b128 v[112:115], v193 offset:128
	s_waitcnt lgkmcnt(3)
	v_pk_mul_f32 v[62:63], v[62:63], v[102:103]
	s_waitcnt lgkmcnt(2)
	v_pk_mul_f32 v[58:59], v[58:59], v[106:107]
	s_waitcnt lgkmcnt(1)
	v_pk_mul_f32 v[54:55], v[54:55], v[110:111]
	s_waitcnt lgkmcnt(0)
	v_pk_mul_f32 v[50:51], v[50:51], v[114:115]
	v_pk_mul_f32 v[60:61], v[60:61], v[100:101]
	v_pk_mul_f32 v[56:57], v[56:57], v[104:105]
	v_pk_mul_f32 v[52:53], v[52:53], v[108:109]
	v_pk_mul_f32 v[48:49], v[48:49], v[112:113]
	v_pk_mul_f32 v[46:47], v[46:47], v[102:103]
	v_pk_mul_f32 v[42:43], v[42:43], v[106:107]
	v_pk_mul_f32 v[38:39], v[38:39], v[110:111]
	v_pk_mul_f32 v[34:35], v[34:35], v[114:115]
	v_pk_mul_f32 v[44:45], v[44:45], v[100:101]
	v_pk_mul_f32 v[40:41], v[40:41], v[104:105]
	v_pk_mul_f32 v[36:37], v[36:37], v[108:109]
	v_pk_mul_f32 v[32:33], v[32:33], v[112:113]
	v_pk_mul_f32 v[30:31], v[30:31], v[102:103]
	v_pk_mul_f32 v[26:27], v[26:27], v[106:107]
	v_pk_mul_f32 v[22:23], v[22:23], v[110:111]
	v_pk_mul_f32 v[18:19], v[18:19], v[114:115]
	v_pk_mul_f32 v[28:29], v[28:29], v[100:101]
	v_pk_mul_f32 v[24:25], v[24:25], v[104:105]
	v_pk_mul_f32 v[20:21], v[20:21], v[108:109]
	v_pk_mul_f32 v[16:17], v[16:17], v[112:113]
	v_pk_mul_f32 v[14:15], v[14:15], v[102:103]
	v_pk_mul_f32 v[10:11], v[10:11], v[106:107]
	v_pk_mul_f32 v[6:7], v[6:7], v[110:111]
	v_pk_mul_f32 v[2:3], v[2:3], v[114:115]
	v_pk_mul_f32 v[12:13], v[12:13], v[100:101]
	v_pk_mul_f32 v[8:9], v[8:9], v[104:105]
	v_pk_mul_f32 v[4:5], v[4:5], v[108:109]
	v_pk_mul_f32 v[0:1], v[0:1], v[112:113]
.LBB0_1487:
	v_cndmask_b32_e64 v208, v64, v208, s[42:43]
	v_mul_f32_e32 v166, 0xbdd53b94, v208
	v_fmamk_f32 v64, v84, 0x3dd53b94, v166
	v_fmamk_f32 v65, v85, 0x3dd53b94, v166
	v_fmamk_f32 v66, v86, 0x3dd53b94, v166
	v_fmamk_f32 v67, v87, 0x3dd53b94, v166
	v_fmamk_f32 v100, v88, 0x3dd53b94, v166
	v_fmamk_f32 v101, v89, 0x3dd53b94, v166
	v_fmamk_f32 v102, v90, 0x3dd53b94, v166
	v_fmamk_f32 v103, v91, 0x3dd53b94, v166
	v_fmamk_f32 v104, v92, 0x3dd53b94, v166
	v_fmamk_f32 v105, v93, 0x3dd53b94, v166
	v_fmamk_f32 v106, v94, 0x3dd53b94, v166
	v_fmamk_f32 v107, v95, 0x3dd53b94, v166
	v_fmamk_f32 v96, v96, 0x3dd53b94, v166
	v_fmamk_f32 v97, v97, 0x3dd53b94, v166
	v_fmamk_f32 v98, v98, 0x3dd53b94, v166
	v_fmamk_f32 v99, v99, 0x3dd53b94, v166
	v_fmamk_f32 v84, v68, 0x3dd53b94, v166
	v_fmamk_f32 v93, v69, 0x3dd53b94, v166
	v_fmamk_f32 v94, v70, 0x3dd53b94, v166
	v_fmamk_f32 v95, v71, 0x3dd53b94, v166
	v_fmamk_f32 v167, v72, 0x3dd53b94, v166
	v_fmamk_f32 v85, v73, 0x3dd53b94, v166
	v_fmamk_f32 v86, v74, 0x3dd53b94, v166
	v_fmamk_f32 v87, v75, 0x3dd53b94, v166
	v_fmamk_f32 v88, v76, 0x3dd53b94, v166
	v_fmamk_f32 v89, v77, 0x3dd53b94, v166
	v_fmamk_f32 v90, v78, 0x3dd53b94, v166
	v_fmamk_f32 v91, v79, 0x3dd53b94, v166
	v_exp_f32_e32 v64, v64
	v_exp_f32_e32 v65, v65
	v_exp_f32_e32 v66, v66
	v_exp_f32_e32 v67, v67
	v_exp_f32_e32 v68, v100
	v_exp_f32_e32 v69, v101
	v_exp_f32_e32 v70, v102
	v_exp_f32_e32 v71, v103
	v_exp_f32_e32 v72, v104
	v_exp_f32_e32 v73, v105
	v_exp_f32_e32 v74, v106
	v_exp_f32_e32 v75, v107
	v_exp_f32_e32 v76, v96
	v_exp_f32_e32 v77, v97
	v_exp_f32_e32 v78, v98
	v_exp_f32_e32 v79, v99
	v_fmamk_f32 v92, v80, 0x3dd53b94, v166
	v_fmamk_f32 v168, v81, 0x3dd53b94, v166
	v_fmamk_f32 v169, v82, 0x3dd53b94, v166
	v_fmac_f32_e32 v166, 0x3dd53b94, v83
	s_waitcnt lgkmcnt(0)
	s_barrier
	ds_read_b128 v[80:83], v202 offset:45568
	ds_read_b128 v[96:99], v202 offset:32768
	ds_read_b128 v[170:173], v202 offset:32800
	v_exp_f32_e32 v85, v85
	v_exp_f32_e32 v86, v86
	v_exp_f32_e32 v87, v87
	s_waitcnt lgkmcnt(1)
	v_mfma_f32_32x32x16_bf16 v[112:127], v[96:99], v[142:145], 0
	v_exp_f32_e32 v88, v88
	v_exp_f32_e32 v89, v89
	v_exp_f32_e32 v90, v90
	v_exp_f32_e32 v91, v91
	v_exp_f32_e32 v92, v92
	v_mfma_f32_32x32x16_bf16 v[96:111], v[80:83], v[142:145], 0
	ds_read_b128 v[80:83], v202 offset:45600
	s_waitcnt lgkmcnt(1)
	v_mfma_f32_32x32x16_bf16 v[112:127], v[170:173], v[138:141], v[112:127]
	v_add_f32_e32 v255, 0, v64
	v_add_f32_e32 v255, v65, v255
	s_waitcnt lgkmcnt(0)
	v_mfma_f32_32x32x16_bf16 v[96:111], v[80:83], v[138:141], v[96:111]
	ds_read_b128 v[80:83], v202 offset:32832
	ds_read_b128 v[170:173], v202 offset:45632
	v_add_f32_e32 v255, v66, v255
	v_add_f32_e32 v255, v67, v255
	s_waitcnt lgkmcnt(1)
	v_mfma_f32_32x32x16_bf16 v[112:127], v[80:83], v[134:137], v[112:127]
	v_add_f32_e32 v255, v68, v255
	v_add_f32_e32 v255, v69, v255
	s_waitcnt lgkmcnt(0)
	v_mfma_f32_32x32x16_bf16 v[96:111], v[170:173], v[134:137], v[96:111]
	ds_read_b128 v[80:83], v202 offset:32864
	ds_read_b128 v[170:173], v202 offset:45664
	v_add_f32_e32 v255, v70, v255
	v_add_f32_e32 v255, v71, v255
	s_waitcnt lgkmcnt(1)
	v_mfma_f32_32x32x16_bf16 v[112:127], v[80:83], v[130:133], v[112:127]
	v_add_f32_e32 v255, v72, v255
	v_add_f32_e32 v255, v73, v255
	s_waitcnt lgkmcnt(0)
	v_mfma_f32_32x32x16_bf16 v[96:111], v[170:173], v[130:133], v[96:111]
	ds_read_b128 v[80:83], v202 offset:32896
	ds_read_b128 v[170:173], v202 offset:45696
	ds_read_b128 v[174:177], v201
	ds_read_b128 v[178:181], v201 offset:32
	v_add_f32_e32 v255, v74, v255
	v_add_f32_e32 v255, v75, v255
	s_waitcnt lgkmcnt(1)
; __device__ __forceinline__ void finishSM(f32x16& p0, f32x16& p1, float alpha, float& l_reg, bf16x8& pa0, bf16x8& pa1, bf16x8& pa2, bf16x8& pa3) {
; #pragma unroll
;     for (int r = 0; r < 16; ++r) p1[r] = __builtin_amdgcn_exp2f(p1[r]);
;     float ps = 0;
; #pragma unroll
;     for (int r = 0; r < 16; ++r) ps += p0[r];
; #pragma unroll
;     for (int r = 0; r < 16; ++r) ps += p1[r];
;     { auto rr = __builtin_amdgcn_permlane32_swap(__float_as_uint(ps), __float_as_uint(ps), false, false);
;       ps = __uint_as_float(rr[0]) + __uint_as_float(rr[1]); }
;     l_reg = l_reg * alpha + ps;
;     ...
;     PK4(p0, 0, pa0); PK4(p0, 8, pa1); PK4(p1, 0, pa2); PK4(p1, 8, pa3);
;     ...
; }
; template <int KB>
; __device__ __forceinline__ void qkt(f32x16& p0, f32x16& p1, const char* K_lds, int r32, int hi, const bf16x8* qr, const char* qbase) {
;     p0 = f32x16{}; p1 = f32x16{};
;     const char* kbp = K_lds + KB * SHM_K + r32 * KROW + hi * 16;
; #pragma unroll
;     for (int d0 = 0; d0 < 12; ++d0) { const char* a = kbp + d0 * 32;
;         bf16x8 b0 = *reinterpret_cast<const bf16x8*>(a);
;         bf16x8 b1 = *reinterpret_cast<const bf16x8*>(a + 32 * KROW);
;         const bf16x8 qf = d0 < 4 ? qr[d0 & 3] : *reinterpret_cast<const bf16x8*>(qbase + (d0 - 4) * 32);
;         p0 = __builtin_amdgcn_mfma_f32_32x32x16_bf16(b0, qf, p0, 0, 0, 0);
;         p1 = __builtin_amdgcn_mfma_f32_32x32x16_bf16(b1, qf, p1, 0, 0, 0); }
; }
	v_mfma_f32_32x32x16_bf16 v[112:127], v[80:83], v[174:177], v[112:127]
	v_mfma_f32_32x32x16_bf16 v[96:111], v[170:173], v[174:177], v[96:111]
	ds_read_b128 v[80:83], v202 offset:32928
	ds_read_b128 v[170:173], v202 offset:45728
	v_add_f32_e32 v255, v76, v255
	v_add_f32_e32 v255, v77, v255
	s_waitcnt lgkmcnt(1)
	v_mfma_f32_32x32x16_bf16 v[112:127], v[80:83], v[178:181], v[112:127]
	v_add_f32_e32 v255, v78, v255
	v_add_f32_e32 v255, v79, v255
	s_waitcnt lgkmcnt(0)
	v_mfma_f32_32x32x16_bf16 v[96:111], v[170:173], v[178:181], v[96:111]
	ds_read_b128 v[80:83], v202 offset:32960
	ds_read_b128 v[170:173], v202 offset:45760
	ds_read_b128 v[174:177], v201 offset:64
	v_add_f32_e32 v255, v85, v255
	v_add_f32_e32 v255, v86, v255
	s_waitcnt lgkmcnt(0)
	v_mfma_f32_32x32x16_bf16 v[112:127], v[80:83], v[174:177], v[112:127]
	v_mfma_f32_32x32x16_bf16 v[96:111], v[170:173], v[174:177], v[96:111]
	ds_read_b128 v[80:83], v202 offset:32992
	ds_read_b128 v[170:173], v202 offset:45792
	ds_read_b128 v[174:177], v201 offset:96
	v_add_f32_e32 v255, v87, v255
	v_add_f32_e32 v255, v88, v255
	s_waitcnt lgkmcnt(0)
	v_mfma_f32_32x32x16_bf16 v[112:127], v[80:83], v[174:177], v[112:127]
	v_mfma_f32_32x32x16_bf16 v[96:111], v[170:173], v[174:177], v[96:111]
	ds_read_b128 v[80:83], v202 offset:33024
	ds_read_b128 v[170:173], v202 offset:45824
	ds_read_b128 v[174:177], v201 offset:128
	v_add_f32_e32 v255, v89, v255
	v_add_f32_e32 v255, v90, v255
	s_waitcnt lgkmcnt(0)
	v_mfma_f32_32x32x16_bf16 v[112:127], v[80:83], v[174:177], v[112:127]
	v_mfma_f32_32x32x16_bf16 v[96:111], v[170:173], v[174:177], v[96:111]
	ds_read_b128 v[80:83], v202 offset:33056
	ds_read_b128 v[170:173], v202 offset:45856
	ds_read_b128 v[174:177], v201 offset:160
	v_add_f32_e32 v255, v91, v255
	v_add_f32_e32 v255, v92, v255
	s_waitcnt lgkmcnt(0)
	v_mfma_f32_32x32x16_bf16 v[112:127], v[80:83], v[174:177], v[112:127]
	v_mfma_f32_32x32x16_bf16 v[96:111], v[170:173], v[174:177], v[96:111]
	ds_read_b128 v[80:83], v202 offset:33088
	ds_read_b128 v[170:173], v202 offset:45888
	ds_read_b128 v[174:177], v201 offset:192
	s_waitcnt lgkmcnt(0)
	v_mfma_f32_32x32x16_bf16 v[112:127], v[80:83], v[174:177], v[112:127]
	v_mfma_f32_32x32x16_bf16 v[96:111], v[170:173], v[174:177], v[96:111]
	ds_read_b128 v[80:83], v202 offset:33120
	ds_read_b128 v[170:173], v202 offset:45920
	ds_read_b128 v[174:177], v201 offset:224
	s_waitcnt lgkmcnt(0)
	v_mfma_f32_32x32x16_bf16 v[112:127], v[80:83], v[174:177], v[112:127]
	v_mfma_f32_32x32x16_bf16 v[96:111], v[170:173], v[174:177], v[96:111]
	v_exp_f32_e32 v83, v95
	v_exp_f32_e32 v95, v166
	v_exp_f32_e32 v80, v84
	v_exp_f32_e32 v81, v93
	v_exp_f32_e32 v82, v94
	v_exp_f32_e32 v84, v167
	v_exp_f32_e32 v93, v168
	v_exp_f32_e32 v94, v169
	v_add_f32_e32 v255, v80, v255
	v_add_f32_e32 v255, v81, v255
	v_add_f32_e32 v255, v82, v255
	v_add_f32_e32 v255, v83, v255
	v_add_f32_e32 v255, v84, v255
	v_add_f32_e32 v255, v93, v255
	v_add_f32_e32 v255, v94, v255
	v_add_f32_e32 v236, v95, v255
	v_mov_b32_e32 v237, v236
	v_cvt_pk_bf16_f32 v166, v64, v65
	v_cvt_pk_bf16_f32 v167, v66, v67
	v_cvt_pk_bf16_f32 v168, v68, v69
	v_cvt_pk_bf16_f32 v169, v70, v71
	v_cvt_pk_bf16_f32 v170, v72, v73
	v_cvt_pk_bf16_f32 v171, v74, v75
	v_cvt_pk_bf16_f32 v172, v76, v77
	v_cvt_pk_bf16_f32 v173, v78, v79
	v_cvt_pk_bf16_f32 v174, v80, v81
	v_cvt_pk_bf16_f32 v175, v82, v83
	v_cvt_pk_bf16_f32 v176, v84, v85
	v_cvt_pk_bf16_f32 v177, v86, v87
	v_cvt_pk_bf16_f32 v178, v88, v89
	v_cvt_pk_bf16_f32 v179, v90, v91
	v_cvt_pk_bf16_f32 v180, v92, v93
	v_cvt_pk_bf16_f32 v181, v94, v95
	s_nop 1
	v_permlane32_swap_b32_e32 v236, v237
	v_permlane32_swap_b32_e32 v166, v168
	v_permlane32_swap_b32_e32 v167, v169
	v_permlane32_swap_b32_e32 v170, v172
	v_permlane32_swap_b32_e32 v171, v173
	v_permlane32_swap_b32_e32 v174, v176
	v_permlane32_swap_b32_e32 v175, v177
	v_permlane32_swap_b32_e32 v178, v180
	v_permlane32_swap_b32_e32 v179, v181
	s_add_i32 s0, s26, 1
	s_cmp_lt_u32 s0, s35
	s_cselect_b64 s[28:29], -1, 0
	s_cmp_ge_u32 s0, s35
	s_cbranch_scc1 .LBB0_1489
	v_add_u32_e32 v146, 0xc0, v213
	v_min_u32_e32 v148, 0x100f, v146
	v_add_u32_e32 v147, 0x40c0, v213
	v_add_u32_e32 v148, s14, v148
	v_cmp_gt_i32_e32 vcc, 16, v146
	s_nop 1
	v_cndmask_b32_e32 v146, v148, v147, vcc
	v_ashrrev_i32_e32 v147, 31, v146
	v_mad_i64_i32 v[158:159], s[0:1], v146, s33, v[184:185]
	v_lshlrev_b64 v[146:147], 12, v[146:147]
	v_lshl_add_u64 v[160:161], v[186:187], 0, v[146:147]
	flat_load_dwordx4 v[146:149], v[160:161] offset:128
	flat_load_dwordx4 v[150:153], v[158:159]
	flat_load_dwordx4 v[154:157], v[158:159] offset:128
	flat_load_dwordx4 v[162:165], v[160:161]
	s_nop 0
	flat_load_dwordx4 v[158:161], v[158:159] offset:256
; __device__ __forceinline__ void mask_tile(f32x16& p0, f32x16& p1, int dq) {
;     const float NEG = -__builtin_inff();
; #pragma unroll
;     for (int r = 0; r < 16; ++r) {
;         const int c = (r & 3) + 8 * (r >> 2);
;         if (dq - c < 0) p0[r] = NEG;
;         if (dq - c - 32 < 0) p1[r] = NEG;
;     }
; }
; template <int VB>
; __device__ __forceinline__ void pv_tile(f32x16* o, int vb0, bf16x8 pa0, bf16x8 pa1, bf16x8 pa2, bf16x8 pa3) {
;     ...
;     PV_D0(0); PV_D0(1); PV_D0(2); PV_D0(3);
.LBB0_1489:
	s_add_i32 s0, s31, 0xbf
	s_cmp_le_i32 s0, s30
	s_cbranch_scc1 .La_pvmax2
	ds_read_b64_tr_b16 v[214:215], v199 offset:0x4000
	ds_read_b64_tr_b16 v[216:217], v199 offset:0x4800
	ds_read_b64_tr_b16 v[218:219], v199 offset:0x5000
	ds_read_b64_tr_b16 v[220:221], v199 offset:0x5800
	ds_read_b64_tr_b16 v[232:233], v199 offset:0x6000
	ds_read_b64_tr_b16 v[234:235], v199 offset:0x6800
	ds_read_b64_tr_b16 v[242:243], v199 offset:0x7000
	ds_read_b64_tr_b16 v[244:245], v199 offset:0x7800
	s_waitcnt lgkmcnt(0)
	s_nop 0
	v_mfma_f32_32x32x16_bf16 v[48:63], v[166:169], v[214:217], v[48:63]
	ds_read_b64_tr_b16 v[214:215], v199 offset:0x4200
	ds_read_b64_tr_b16 v[216:217], v199 offset:0x4a00
	v_mfma_f32_32x32x16_bf16 v[48:63], v[170:173], v[218:221], v[48:63]
	ds_read_b64_tr_b16 v[218:219], v199 offset:0x5200
	ds_read_b64_tr_b16 v[220:221], v199 offset:0x5a00
	v_mfma_f32_32x32x16_bf16 v[48:63], v[174:177], v[232:235], v[48:63]
	ds_read_b64_tr_b16 v[232:233], v199 offset:0x6200
	ds_read_b64_tr_b16 v[234:235], v199 offset:0x6a00
	v_mfma_f32_32x32x16_bf16 v[48:63], v[178:181], v[242:245], v[48:63]
	ds_read_b64_tr_b16 v[242:243], v199 offset:0x7200
	ds_read_b64_tr_b16 v[244:245], v199 offset:0x7a00
	s_waitcnt lgkmcnt(0)
	v_mfma_f32_32x32x16_bf16 v[32:47], v[166:169], v[214:217], v[32:47]
	ds_read_b64_tr_b16 v[214:215], v199 offset:0x4400
	ds_read_b64_tr_b16 v[216:217], v199 offset:0x4c00
	v_mfma_f32_32x32x16_bf16 v[32:47], v[170:173], v[218:221], v[32:47]
	ds_read_b64_tr_b16 v[218:219], v199 offset:0x5400
	ds_read_b64_tr_b16 v[220:221], v199 offset:0x5c00
	v_mfma_f32_32x32x16_bf16 v[32:47], v[174:177], v[232:235], v[32:47]
	ds_read_b64_tr_b16 v[232:233], v199 offset:0x6400
	ds_read_b64_tr_b16 v[234:235], v199 offset:0x6c00
	v_mfma_f32_32x32x16_bf16 v[32:47], v[178:181], v[242:245], v[32:47]
	ds_read_b64_tr_b16 v[242:243], v199 offset:0x7400
	ds_read_b64_tr_b16 v[244:245], v199 offset:0x7c00
	s_waitcnt lgkmcnt(0)
	v_mfma_f32_32x32x16_bf16 v[16:31], v[166:169], v[214:217], v[16:31]
	ds_read_b64_tr_b16 v[214:215], v199 offset:0x4600
	ds_read_b64_tr_b16 v[216:217], v199 offset:0x4e00
	v_mfma_f32_32x32x16_bf16 v[16:31], v[170:173], v[218:221], v[16:31]
	ds_read_b64_tr_b16 v[218:219], v199 offset:0x5600
	ds_read_b64_tr_b16 v[220:221], v199 offset:0x5e00
	v_mfma_f32_32x32x16_bf16 v[16:31], v[174:177], v[232:235], v[16:31]
	ds_read_b64_tr_b16 v[232:233], v199 offset:0x6600
	ds_read_b64_tr_b16 v[234:235], v199 offset:0x6e00
	v_mfma_f32_32x32x16_bf16 v[16:31], v[178:181], v[242:245], v[16:31]
	ds_read_b64_tr_b16 v[242:243], v199 offset:0x7600
	ds_read_b64_tr_b16 v[244:245], v199 offset:0x7e00
	s_waitcnt lgkmcnt(0)
	v_mfma_f32_32x32x16_bf16 v[0:15], v[166:169], v[214:217], v[0:15]
	s_add_i32 s0, s31, 0xbf
	s_cmp_le_i32 s0, s30
	v_mfma_f32_32x32x16_bf16 v[0:15], v[170:173], v[218:221], v[0:15]
	v_mfma_f32_32x32x16_bf16 v[0:15], v[174:177], v[232:235], v[0:15]
	v_mfma_f32_32x32x16_bf16 v[0:15], v[178:181], v[242:245], v[0:15]
	s_cbranch_scc1 .LBB0_1491
	v_cmp_gt_i32_e64 s[94:95], 26, v209
	v_cmp_gt_i32_e64 s[96:97], 27, v209
	v_cmp_gt_i32_e64 s[92:93], 25, v209
	s_and_b64 s[94:95], s[96:97], s[94:95]
	v_cmp_gt_i32_e64 s[90:91], 24, v209
	s_and_b64 s[92:93], s[94:95], s[92:93]
	v_cmp_gt_i32_e64 s[88:89], 19, v209
	s_and_b64 s[90:91], s[92:93], s[90:91]
	v_cmp_gt_i32_e64 s[86:87], 18, v209
	s_and_b64 s[88:89], s[90:91], s[88:89]
	v_cmp_gt_i32_e64 s[84:85], 17, v209
	s_and_b64 s[86:87], s[88:89], s[86:87]
	v_cmp_gt_i32_e64 s[82:83], 16, v209
	s_and_b64 s[84:85], s[86:87], s[84:85]
	v_cmp_gt_i32_e64 s[80:81], 11, v209
	s_and_b64 s[82:83], s[84:85], s[82:83]
	v_cmp_gt_i32_e64 s[78:79], 10, v209
	s_and_b64 s[80:81], s[82:83], s[80:81]
	v_cmp_gt_i32_e64 s[76:77], 9, v209
	s_and_b64 s[78:79], s[80:81], s[78:79]
	v_cmp_gt_i32_e64 s[74:75], 8, v209
	s_and_b64 s[76:77], s[78:79], s[76:77]
	v_cmp_gt_i32_e64 s[72:73], 3, v209
	s_and_b64 s[74:75], s[76:77], s[74:75]
	v_cmp_gt_i32_e64 s[70:71], 2, v209
	s_and_b64 s[72:73], s[74:75], s[72:73]
	v_cmp_gt_i32_e64 s[6:7], 1, v209
	s_and_b64 s[70:71], s[72:73], s[70:71]
	v_cmp_gt_i32_e64 s[4:5], 0, v209
	s_and_b64 s[6:7], s[70:71], s[6:7]
	s_and_b64 s[4:5], s[6:7], s[4:5]
	v_cmp_gt_i32_e64 s[68:69], 58, v209
	v_cndmask_b32_e64 v112, v112, v228, s[4:5]
	v_cmp_gt_i32_e64 s[4:5], 59, v209
	v_cmp_gt_i32_e64 s[66:67], 57, v209
	v_cmp_gt_i32_e64 s[64:65], 56, v209
	v_cndmask_b32_e64 v111, v111, v228, s[4:5]
	s_and_b64 s[4:5], s[4:5], s[68:69]
	v_cndmask_b32_e64 v110, v110, v228, s[4:5]
	s_and_b64 s[4:5], s[4:5], s[66:67]
	v_cmp_gt_i32_e64 s[62:63], 51, v209
	v_cndmask_b32_e64 v109, v109, v228, s[4:5]
	s_and_b64 s[4:5], s[4:5], s[64:65]
	v_cmp_gt_i32_e64 s[60:61], 50, v209
	v_cndmask_b32_e64 v108, v108, v228, s[4:5]
	s_and_b64 s[4:5], s[4:5], s[62:63]
	v_cmp_gt_i32_e64 s[58:59], 49, v209
	v_cndmask_b32_e64 v107, v107, v228, s[4:5]
	s_and_b64 s[4:5], s[4:5], s[60:61]
	v_cmp_gt_i32_e64 s[56:57], 48, v209
	v_cndmask_b32_e64 v106, v106, v228, s[4:5]
	s_and_b64 s[4:5], s[4:5], s[58:59]
	v_cmp_gt_i32_e64 s[54:55], 43, v209
	v_cndmask_b32_e64 v105, v105, v228, s[4:5]
	s_and_b64 s[4:5], s[4:5], s[56:57]
	v_cmp_gt_i32_e64 s[52:53], 42, v209
	v_cndmask_b32_e64 v104, v104, v228, s[4:5]
	s_and_b64 s[4:5], s[4:5], s[54:55]
	v_cmp_gt_i32_e64 s[50:51], 41, v209
	v_cndmask_b32_e64 v103, v103, v228, s[4:5]
	s_and_b64 s[4:5], s[4:5], s[52:53]
	v_cmp_gt_i32_e64 s[46:47], 40, v209
	v_cndmask_b32_e64 v102, v102, v228, s[4:5]
	s_and_b64 s[4:5], s[4:5], s[50:51]
	v_cmp_gt_i32_e64 s[44:45], 35, v209
	v_cndmask_b32_e64 v101, v101, v228, s[4:5]
	s_and_b64 s[4:5], s[4:5], s[46:47]
	v_cmp_gt_i32_e64 s[42:43], 34, v209
	v_cndmask_b32_e64 v100, v100, v228, s[4:5]
	s_and_b64 s[4:5], s[4:5], s[44:45]
	v_cmp_gt_i32_e64 s[0:1], 33, v209
	v_cndmask_b32_e64 v99, v99, v228, s[4:5]
	s_and_b64 s[4:5], s[4:5], s[42:43]
	v_cmp_gt_i32_e32 vcc, 32, v209
	s_and_b64 s[0:1], s[4:5], s[0:1]
	s_and_b64 vcc, s[0:1], vcc
	v_cndmask_b32_e64 v127, v127, v228, s[96:97]
	s_mov_b32 s97, 0x41000000
	v_cndmask_b32_e64 v126, v126, v228, s[94:95]
	v_cndmask_b32_e64 v125, v125, v228, s[92:93]
	v_cndmask_b32_e64 v124, v124, v228, s[90:91]
	v_cndmask_b32_e64 v123, v123, v228, s[88:89]
	v_cndmask_b32_e64 v122, v122, v228, s[86:87]
	v_cndmask_b32_e64 v121, v121, v228, s[84:85]
	v_cndmask_b32_e64 v120, v120, v228, s[82:83]
	v_cndmask_b32_e64 v119, v119, v228, s[80:81]
	v_cndmask_b32_e64 v118, v118, v228, s[78:79]
	v_cndmask_b32_e64 v117, v117, v228, s[76:77]
	v_cndmask_b32_e64 v116, v116, v228, s[74:75]
	v_cndmask_b32_e64 v115, v115, v228, s[72:73]
	v_cndmask_b32_e64 v114, v114, v228, s[70:71]
	v_cndmask_b32_e64 v113, v113, v228, s[6:7]
	v_cndmask_b32_e64 v98, v98, v228, s[4:5]
	v_cndmask_b32_e64 v97, v97, v228, s[0:1]
	v_cndmask_b32_e32 v96, v96, v228, vcc

.La_b1_2:
	s_andn2_b64 vcc, exec, s[28:29]
	s_waitcnt lgkmcnt(0)
	s_barrier
	s_cbranch_vccnz .LBB0_1493
	s_waitcnt vmcnt(0)
	s_waitcnt vmcnt(0)
	ds_write_b128 v204, v[162:165] offset:16384
	ds_write_b128 v204, v[146:149] offset:17408
	ds_write_b128 v192, v[150:153] offset:58368
	ds_write_b128 v192, v[154:157] offset:58496
	ds_write_b128 v192, v[158:161] offset:58624

; __device__ __forceinline__ void partialSM(f32x16& p0, f32x16& p1, float& m_reg, float& mn, float& alpha) {
;     float pmax = p0[0];
; #pragma unroll
;     for (int r = 1; r < 16; ++r) pmax = fmaxf(pmax, p0[r]);
; #pragma unroll
;     for (int r = 0; r < 16; ++r) pmax = fmaxf(pmax, p1[r]);
;     { auto rr = __builtin_amdgcn_permlane32_swap(__float_as_uint(pmax), __float_as_uint(pmax), false, false);
;       pmax = fmaxf(__uint_as_float(rr[0]), __uint_as_float(rr[1])); }
;     constexpr float C2 = 1.4426950408889634f * SCALE;
;     if (__builtin_expect(__all((pmax - m_reg) * SCALE <= THR), 1)) { mn = m_reg; alpha = 1.f; }
;     else { mn = fmaxf(m_reg, pmax); alpha = __builtin_amdgcn_exp2f((m_reg - mn) * C2); m_reg = mn; }
; template <int VB>
; __device__ __forceinline__ void pv_tile(f32x16* o, int vb0, bf16x8 pa0, bf16x8 pa1, bf16x8 pa2, bf16x8 pa3) {
;     ...
;     PV_D0(0); PV_D0(1); PV_D0(2); PV_D0(3);
.La_pvmax1:
	ds_read_b64_tr_b16 v[112:113], v199 offset:0
	ds_read_b64_tr_b16 v[114:115], v199 offset:0x800
	ds_read_b64_tr_b16 v[116:117], v199 offset:0x1000
	ds_read_b64_tr_b16 v[118:119], v199 offset:0x1800
	ds_read_b64_tr_b16 v[120:121], v199 offset:0x2000
	ds_read_b64_tr_b16 v[122:123], v199 offset:0x2800
	ds_read_b64_tr_b16 v[124:125], v199 offset:0x3000
	ds_read_b64_tr_b16 v[126:127], v199 offset:0x3800
	s_waitcnt lgkmcnt(0)
	s_nop 0
	v_mfma_f32_32x32x16_bf16 v[48:63], v[64:67], v[112:115], v[48:63]
	v_max_f32_e32 v250, v85, v85
	v_max_f32_e32 v251, v84, v84
	ds_read_b64_tr_b16 v[112:113], v199 offset:0x200
	ds_read_b64_tr_b16 v[114:115], v199 offset:0xa00
	v_mfma_f32_32x32x16_bf16 v[48:63], v[100:103], v[116:119], v[48:63]
	v_max_f32_e32 v250, v251, v250
	v_max3_f32 v250, v250, v86, v87
	ds_read_b64_tr_b16 v[116:117], v199 offset:0x1200
	ds_read_b64_tr_b16 v[118:119], v199 offset:0x1a00
	v_mfma_f32_32x32x16_bf16 v[48:63], v[104:107], v[120:123], v[48:63]
	v_max3_f32 v250, v250, v88, v89
	v_max3_f32 v250, v250, v90, v91
	ds_read_b64_tr_b16 v[120:121], v199 offset:0x2200
	ds_read_b64_tr_b16 v[122:123], v199 offset:0x2a00
	v_mfma_f32_32x32x16_bf16 v[48:63], v[108:111], v[124:127], v[48:63]
	v_max3_f32 v250, v250, v92, v93
	v_max3_f32 v250, v250, v94, v95
	ds_read_b64_tr_b16 v[124:125], v199 offset:0x3200
	ds_read_b64_tr_b16 v[126:127], v199 offset:0x3a00
	s_waitcnt lgkmcnt(0)
	v_mfma_f32_32x32x16_bf16 v[32:47], v[64:67], v[112:115], v[32:47]
	v_max3_f32 v250, v250, v96, v97
	v_max3_f32 v250, v250, v98, v99
	ds_read_b64_tr_b16 v[112:113], v199 offset:0x400
	ds_read_b64_tr_b16 v[114:115], v199 offset:0xc00
	v_mfma_f32_32x32x16_bf16 v[32:47], v[100:103], v[116:119], v[32:47]
	v_max3_f32 v250, v250, v68, v69
	v_max3_f32 v250, v250, v70, v71
	ds_read_b64_tr_b16 v[116:117], v199 offset:0x1400
	ds_read_b64_tr_b16 v[118:119], v199 offset:0x1c00
	v_mfma_f32_32x32x16_bf16 v[32:47], v[104:107], v[120:123], v[32:47]
	v_max3_f32 v250, v250, v72, v73
	v_max3_f32 v250, v250, v74, v75
	ds_read_b64_tr_b16 v[120:121], v199 offset:0x2400
	ds_read_b64_tr_b16 v[122:123], v199 offset:0x2c00
	v_mfma_f32_32x32x16_bf16 v[32:47], v[108:111], v[124:127], v[32:47]
	v_max3_f32 v250, v250, v76, v77
	v_max3_f32 v250, v250, v78, v79
	ds_read_b64_tr_b16 v[124:125], v199 offset:0x3400
	ds_read_b64_tr_b16 v[126:127], v199 offset:0x3c00
	s_waitcnt lgkmcnt(0)
	v_mfma_f32_32x32x16_bf16 v[16:31], v[64:67], v[112:115], v[16:31]
	v_max3_f32 v250, v250, v80, v81
	v_max3_f32 v250, v250, v82, v83
	ds_read_b64_tr_b16 v[112:113], v199 offset:0x600
	ds_read_b64_tr_b16 v[114:115], v199 offset:0xe00
	v_mfma_f32_32x32x16_bf16 v[16:31], v[100:103], v[116:119], v[16:31]
	v_mov_b32_e32 v251, v250
	s_nop 1
	v_permlane32_swap_b32_e32 v250, v251
	v_max_f32_e32 v251, v251, v251
	ds_read_b64_tr_b16 v[116:117], v199 offset:0x1600
	ds_read_b64_tr_b16 v[118:119], v199 offset:0x1e00
	v_mfma_f32_32x32x16_bf16 v[16:31], v[104:107], v[120:123], v[16:31]
	v_max_f32_e32 v250, v250, v250
	v_max_f32_e32 v250, v250, v251
	ds_read_b64_tr_b16 v[120:121], v199 offset:0x2600
	ds_read_b64_tr_b16 v[122:123], v199 offset:0x2e00
	v_mfma_f32_32x32x16_bf16 v[16:31], v[108:111], v[124:127], v[16:31]
	v_sub_f32_e32 v251, v250, v208
	v_mul_f32_e32 v251, 0x3d93cd3a, v251
	ds_read_b64_tr_b16 v[124:125], v199 offset:0x3600
	ds_read_b64_tr_b16 v[126:127], v199 offset:0x3e00
	s_waitcnt lgkmcnt(0)
	v_mfma_f32_32x32x16_bf16 v[0:15], v[64:67], v[112:115], v[0:15]
	v_cmp_ge_f32_e32 vcc, s97, v251
	v_max_f32_e32 v251, v208, v208
	v_mfma_f32_32x32x16_bf16 v[0:15], v[100:103], v[116:119], v[0:15]
	v_max_f32_e32 v250, v251, v250
	v_sub_f32_e32 v251, v208, v250
	v_mfma_f32_32x32x16_bf16 v[0:15], v[104:107], v[120:123], v[0:15]
	v_mul_f32_e32 v251, 0x3dd53b94, v251
	v_exp_f32_e32 v251, v251
	v_mfma_f32_32x32x16_bf16 v[0:15], v[108:111], v[124:127], v[0:15]
	s_cmp_eq_u64 vcc, exec
	s_cselect_b64 s[42:43], -1, 0
	v_mov_b32_e32 v64, v250
	v_mov_b32_e32 v65, v251
	s_branch .La_b1_1
; __device__ __forceinline__ void partialSM(f32x16& p0, f32x16& p1, float& m_reg, float& mn, float& alpha) {
;     float pmax = p0[0];
; #pragma unroll
;     for (int r = 1; r < 16; ++r) pmax = fmaxf(pmax, p0[r]);
; #pragma unroll
;     for (int r = 0; r < 16; ++r) pmax = fmaxf(pmax, p1[r]);
;     { auto rr = __builtin_amdgcn_permlane32_swap(__float_as_uint(pmax), __float_as_uint(pmax), false, false);
;       pmax = fmaxf(__uint_as_float(rr[0]), __uint_as_float(rr[1])); }
;     constexpr float C2 = 1.4426950408889634f * SCALE;
;     if (__builtin_expect(__all((pmax - m_reg) * SCALE <= THR), 1)) { mn = m_reg; alpha = 1.f; }
; template <int VB>
; __device__ __forceinline__ void pv_tile(f32x16* o, int vb0, bf16x8 pa0, bf16x8 pa1, bf16x8 pa2, bf16x8 pa3) {
;     ...
;     PV_D0(0); PV_D0(1); PV_D0(2); PV_D0(3);
.La_pvmax2:
	ds_read_b64_tr_b16 v[214:215], v199 offset:0x4000
	ds_read_b64_tr_b16 v[216:217], v199 offset:0x4800
	ds_read_b64_tr_b16 v[218:219], v199 offset:0x5000
	ds_read_b64_tr_b16 v[220:221], v199 offset:0x5800
	ds_read_b64_tr_b16 v[232:233], v199 offset:0x6000
	ds_read_b64_tr_b16 v[234:235], v199 offset:0x6800
	ds_read_b64_tr_b16 v[242:243], v199 offset:0x7000
	ds_read_b64_tr_b16 v[244:245], v199 offset:0x7800
	s_waitcnt lgkmcnt(0)
	s_nop 0
	v_mfma_f32_32x32x16_bf16 v[48:63], v[166:169], v[214:217], v[48:63]
	v_max_f32_e32 v250, v113, v113
	v_max_f32_e32 v251, v112, v112
	ds_read_b64_tr_b16 v[214:215], v199 offset:0x4200
	ds_read_b64_tr_b16 v[216:217], v199 offset:0x4a00
	v_mfma_f32_32x32x16_bf16 v[48:63], v[170:173], v[218:221], v[48:63]
	v_max_f32_e32 v250, v251, v250
	v_max3_f32 v250, v250, v114, v115
	ds_read_b64_tr_b16 v[218:219], v199 offset:0x5200
	ds_read_b64_tr_b16 v[220:221], v199 offset:0x5a00
	v_mfma_f32_32x32x16_bf16 v[48:63], v[174:177], v[232:235], v[48:63]
	v_max3_f32 v250, v250, v116, v117
	v_max3_f32 v250, v250, v118, v119
	ds_read_b64_tr_b16 v[232:233], v199 offset:0x6200
	ds_read_b64_tr_b16 v[234:235], v199 offset:0x6a00
	v_mfma_f32_32x32x16_bf16 v[48:63], v[178:181], v[242:245], v[48:63]
	v_max3_f32 v250, v250, v120, v121
	v_max3_f32 v250, v250, v122, v123
	ds_read_b64_tr_b16 v[242:243], v199 offset:0x7200
	ds_read_b64_tr_b16 v[244:245], v199 offset:0x7a00
	s_waitcnt lgkmcnt(0)
	v_mfma_f32_32x32x16_bf16 v[32:47], v[166:169], v[214:217], v[32:47]
	v_max3_f32 v250, v250, v124, v125
	v_max3_f32 v250, v250, v126, v127
	ds_read_b64_tr_b16 v[214:215], v199 offset:0x4400
	ds_read_b64_tr_b16 v[216:217], v199 offset:0x4c00
	v_mfma_f32_32x32x16_bf16 v[32:47], v[170:173], v[218:221], v[32:47]
	v_max3_f32 v250, v250, v96, v97
	v_max3_f32 v250, v250, v98, v99
	ds_read_b64_tr_b16 v[218:219], v199 offset:0x5400
	ds_read_b64_tr_b16 v[220:221], v199 offset:0x5c00
	v_mfma_f32_32x32x16_bf16 v[32:47], v[174:177], v[232:235], v[32:47]
	v_max3_f32 v250, v250, v100, v101
	v_max3_f32 v250, v250, v102, v103
	ds_read_b64_tr_b16 v[232:233], v199 offset:0x6400
	ds_read_b64_tr_b16 v[234:235], v199 offset:0x6c00
	v_mfma_f32_32x32x16_bf16 v[32:47], v[178:181], v[242:245], v[32:47]
	v_max3_f32 v250, v250, v104, v105
	v_max3_f32 v250, v250, v106, v107
	ds_read_b64_tr_b16 v[242:243], v199 offset:0x7400
	ds_read_b64_tr_b16 v[244:245], v199 offset:0x7c00
	s_waitcnt lgkmcnt(0)
	v_mfma_f32_32x32x16_bf16 v[16:31], v[166:169], v[214:217], v[16:31]
	v_max3_f32 v250, v250, v108, v109
	v_max3_f32 v250, v250, v110, v111
	ds_read_b64_tr_b16 v[214:215], v199 offset:0x4600
	ds_read_b64_tr_b16 v[216:217], v199 offset:0x4e00
	v_mfma_f32_32x32x16_bf16 v[16:31], v[170:173], v[218:221], v[16:31]
	v_mov_b32_e32 v251, v250
	s_nop 1
	v_permlane32_swap_b32_e32 v250, v251
	v_max_f32_e32 v251, v251, v251
	ds_read_b64_tr_b16 v[218:219], v199 offset:0x5600
	ds_read_b64_tr_b16 v[220:221], v199 offset:0x5e00
	v_mfma_f32_32x32x16_bf16 v[16:31], v[174:177], v[232:235], v[16:31]
	v_max_f32_e32 v250, v250, v250
	v_max_f32_e32 v250, v250, v251
	ds_read_b64_tr_b16 v[232:233], v199 offset:0x6600
	ds_read_b64_tr_b16 v[234:235], v199 offset:0x6e00
	v_mfma_f32_32x32x16_bf16 v[16:31], v[178:181], v[242:245], v[16:31]
	v_sub_f32_e32 v251, v250, v208
	v_mul_f32_e32 v251, 0x3d93cd3a, v251
	ds_read_b64_tr_b16 v[242:243], v199 offset:0x7600
	ds_read_b64_tr_b16 v[244:245], v199 offset:0x7e00
	s_waitcnt lgkmcnt(0)
	v_mfma_f32_32x32x16_bf16 v[0:15], v[166:169], v[214:217], v[0:15]
	v_cmp_ge_f32_e32 vcc, s97, v251
	s_cmp_eq_u64 vcc, exec
	v_mfma_f32_32x32x16_bf16 v[0:15], v[170:173], v[218:221], v[0:15]
	s_cselect_b64 s[42:43], -1, 0
	v_mfma_f32_32x32x16_bf16 v[0:15], v[174:177], v[232:235], v[0:15]
	v_mfma_f32_32x32x16_bf16 v[0:15], v[178:181], v[242:245], v[0:15]
	v_mov_b32_e32 v166, v250
	v_mov_b32_e32 v167, v251
	s_branch .La_b1_2
	s_nop 0
	s_nop 0
	s_nop 0
	s_nop 0
	s_nop 0
	s_nop 0
	s_nop 0

; __global__ void __launch_bounds__(512, 2) fwd_megakernel(Params P) {
	.amdhsa_kernel _Z14fwd_megakernel6Params
		.amdhsa_group_segment_fixed_size 0
		.amdhsa_private_segment_fixed_size 0
		.amdhsa_kernarg_size 432
		.amdhsa_user_sgpr_count 2
		.amdhsa_user_sgpr_dispatch_ptr 0
		.amdhsa_user_sgpr_queue_ptr 0
		.amdhsa_user_sgpr_kernarg_segment_ptr 1
		.amdhsa_user_sgpr_dispatch_id 0
		.amdhsa_user_sgpr_kernarg_preload_length 0
		.amdhsa_user_sgpr_kernarg_preload_offset 0
		.amdhsa_user_sgpr_private_segment_size 0
		.amdhsa_uses_dynamic_stack 0
		.amdhsa_enable_private_segment 0
		.amdhsa_system_sgpr_workgroup_id_x 1
		.amdhsa_system_sgpr_workgroup_id_y 0
		.amdhsa_system_sgpr_workgroup_id_z 0
		.amdhsa_system_sgpr_workgroup_info 0
		.amdhsa_system_vgpr_workitem_id 2
		.amdhsa_next_free_vgpr 256
		.amdhsa_next_free_sgpr 98
		.amdhsa_accum_offset 256
		.amdhsa_reserve_vcc 1
		.amdhsa_float_round_mode_32 0
		.amdhsa_float_round_mode_16_64 0
		.amdhsa_float_denorm_mode_32 3
		.amdhsa_float_denorm_mode_16_64 3
		.amdhsa_dx10_clamp 1
		.amdhsa_ieee_mode 1
		.amdhsa_fp16_overflow 0
		.amdhsa_tg_split 0
		.amdhsa_exception_fp_ieee_invalid_op 0
		.amdhsa_exception_fp_denorm_src 0
		.amdhsa_exception_fp_ieee_div_zero 0
		.amdhsa_exception_fp_ieee_overflow 0
		.amdhsa_exception_fp_ieee_underflow 0
		.amdhsa_exception_fp_ieee_inexact 0
		.amdhsa_exception_int_div_zero 0
	.end_amdhsa_kernel

; __global__ void __launch_bounds__(512, 2) fwd_megakernel(Params P) {
amdhsa.kernels:
  - .agpr_count:     0
    .args:
      - .offset:         0
        .size:           176
        .value_kind:     by_value
      - .offset:         176
        .size:           4
        .value_kind:     hidden_block_count_x
      - .offset:         180
        .size:           4
        .value_kind:     hidden_block_count_y
      - .offset:         184
        .size:           4
        .value_kind:     hidden_block_count_z
      - .offset:         188
        .size:           2
        .value_kind:     hidden_group_size_x
      - .offset:         190
        .size:           2
        .value_kind:     hidden_group_size_y
      - .offset:         192
        .size:           2
        .value_kind:     hidden_group_size_z
      - .offset:         194
        .size:           2
        .value_kind:     hidden_remainder_x
      - .offset:         196
        .size:           2
        .value_kind:     hidden_remainder_y
      - .offset:         198
        .size:           2
        .value_kind:     hidden_remainder_z
      - .offset:         216
        .size:           8
        .value_kind:     hidden_global_offset_x
      - .offset:         224
        .size:           8
        .value_kind:     hidden_global_offset_y
      - .offset:         232
        .size:           8
        .value_kind:     hidden_global_offset_z
      - .offset:         240
        .size:           2
        .value_kind:     hidden_grid_dims
      - .offset:         264
        .size:           8
        .value_kind:     hidden_multigrid_sync_arg
      - .offset:         296
        .size:           4
        .value_kind:     hidden_dynamic_lds_size
    .group_segment_fixed_size: 0
    .kernarg_segment_align: 8
    .kernarg_segment_size: 432
    .language:       OpenCL C
    .language_version:
      - 2
      - 0
    .max_flat_workgroup_size: 512
    .name:           _Z14fwd_megakernel6Params
    .private_segment_fixed_size: 0
    .sgpr_count:     104
    .sgpr_spill_count: 267
    .symbol:         _Z14fwd_megakernel6Params.kd
    .uniform_work_group_size: 1
    .uses_dynamic_stack: false
    .vgpr_count:     256
    .vgpr_spill_count: 0
    .wavefront_size: 64
